# norm0 to FFN-in seam also on per-block counters, with a weight-copy completion counter standing in for the grid barrier (6 of 10 seams per layer now group syncs)
# speedup vs baseline: 1.0664x; 1.0161x over previous
.LBB0_263:
	s_mul_i32 s3, s29, s28
	s_ashr_i32 s29, s28, 31
	s_mov_b64 s[4:5], 0xe900100
	s_cmpk_eq_i32 s28, 0x100
	v_writelane_b32 v255, s4, 1
	s_mul_i32 s3, s3, s2
	s_cselect_b64 s[92:93], -1, 0
	v_writelane_b32 v255, s5, 2
	s_add_i32 s2, 0, 0x23f00
	v_writelane_b32 v255, s2, 3
	s_add_i32 s2, 0, 0x23f04
	v_writelane_b32 v255, s2, 4
	s_add_i32 s2, 0, 0x23f10
	s_ashr_i32 s83, s82, 31
	v_writelane_b32 v255, s2, 5
	s_lshl_b64 s[84:85], s[82:83], 11
	s_lshl_b64 s[34:35], s[82:83], 12
	v_writelane_b32 v255, s82, 6
	v_mbcnt_lo_u32_b32 v0, -1, 0
	v_mbcnt_hi_u32_b32 v182, -1, v0
	v_writelane_b32 v255, s83, 7
	v_writelane_b32 v255, s84, 8
	s_mov_b32 s39, 0
	v_and_b32_e32 v0, 64, v182
	v_writelane_b32 v255, s85, 9
	v_writelane_b32 v255, s92, 10
	v_writelane_b32 v255, s39, 45
	v_writelane_b32 v255, s39, 46
	v_writelane_b32 v255, s39, 47
	v_writelane_b32 v255, s39, 48
	v_mov_b32_e32 v145, 0
	s_movk_i32 s67, 0x1000
	s_movk_i32 s69, 0xfff
	s_mov_b32 s73, 0xff000000
	s_mov_b64 s[94:95], 0x1000
	v_mov_b32_e32 v146, 0x358637bd
	s_mov_b32 s72, 0x800000
	s_mov_b32 s74, 0xf7800000
	s_movk_i32 s75, 0x1fff
	v_mov_b32_e32 v185, 0x1000
	v_mov_b32_e32 v186, 0x2000
	v_mov_b32_e32 v189, 1
	s_mov_b32 s76, 0x10000
	s_mov_b32 s77, 0x18000
	s_mov_b64 s[48:49], 0x80
	s_mov_b32 s86, 0x8000
	s_movk_i32 s68, 0x1600
	s_mov_b32 s87, 0x40000
	s_mov_b32 s90, 0x48000
	s_mov_b32 s78, 0x50000
	s_mov_b32 s79, 0x58000
	s_mov_b32 s52, 0x3e000000
	s_mov_b32 s66, 0x3c800000
	s_add_i32 s80, 0, 0x43c
	s_add_i32 s81, 0, 60
	v_add_u32_e32 v183, 64, v0
	v_xor_b32_e32 v188, 1, v182
	v_xor_b32_e32 v254, 2, v182
	v_xor_b32_e32 v187, 16, v182
	v_xor_b32_e32 v184, 32, v182
	v_mov_b64_e32 v[148:149], 0x2bf
	v_mov_b64_e32 v[150:151], 0x100
	v_mov_b64_e32 v[152:153], 0xff
	v_mov_b32_e32 v194, 0xcf
	v_mov_b32_e32 v195, 0x3cf
	v_mov_b32_e32 v196, 0xdf
	v_mov_b32_e32 v197, 0x3df
	v_mov_b32_e32 v198, 0xef
	v_mov_b32_e32 v199, 0x3ef
	v_mov_b32_e32 v200, 0xff
	v_mov_b32_e32 v201, 0x3ff
	v_mov_b32_e32 v202, 0xf149f2ca
	s_mov_b32 s70, s39
	v_writelane_b32 v255, s93, 11
	s_branch .LBB0_265

.Lxb_noinv_1:
	v_cmp_eq_u32_e32 vcc, 0, v0
	s_and_saveexec_b64 s[0:1], vcc
	s_cbranch_execz .LBB0_332
	s_load_dwordx2 s[12:13], s[8:9], 0x98
	v_readlane_b32 s14, v255, 0
	v_readlane_b32 s15, v255, 48
	s_nop 0
	s_lshr_b32 s24, s14, 3
	s_and_b32 s24, s24, 7
	s_and_b32 s27, s14, 6
	s_lshl_b32 s27, s27, 2
	s_or_b32 s27, s27, s24
	s_and_b32 s30, s14, 3
	s_lshl_b32 s30, s30, 3
	s_or_b32 s30, s30, s24
	s_lshl_b32 s27, s27, 7
	s_add_u32 s27, s27, 0xc000
	v_readlane_b32 s35, v255, 45
	s_nop 0
	s_lshl_b32 s35, s35, 4
	s_add_u32 s15, s15, 8
	v_writelane_b32 v255, s15, 48
	v_mov_b32_e32 v0, s27
	s_waitcnt lgkmcnt(0)
	global_atomic_add v0, v189, s[12:13]
	v_mov_b32_e32 v7, s27
	s_mov_b32 s32, 0
	v_mov_b32_e32 v10, 0xd000
.Lgs_poll_b1:
	global_load_dword v6, v7, s[12:13] sc1
	global_load_dword v12, v10, s[12:13] sc1
	s_waitcnt vmcnt(0)
	v_readfirstlane_b32 s34, v6
	v_readfirstlane_b32 s37, v12
	s_nop 0
	s_cmp_ge_u32 s34, s15
	s_cselect_b32 s34, 1, 0
	s_cmp_ge_u32 s37, s35
	s_cselect_b32 s37, 1, 0
	s_and_b32 s34, s34, s37
	s_cmp_lg_u32 s34, 0
	s_cbranch_scc1 .Lgs_done_b1
	s_sleep 1
	s_add_u32 s32, s32, 1
	s_cmp_lt_u32 s32, 0x2000
	s_cbranch_scc1 .Lgs_poll_b1
.Lgs_done_b1:
.LBB0_332:
	s_or_b64 exec, exec, s[0:1]
	s_cmp_lg_u32 s70, 3
	s_cselect_b64 s[0:1], -1, 0
	v_writelane_b32 v255, s0, 14
	s_lshl_b32 s2, s70, 17
	s_lshl_b64 s[10:11], s[70:71], 3
	v_writelane_b32 v255, s1, 15
	s_mov_b64 s[12:13], 0
	v_readlane_b32 s0, v255, 12
	v_readlane_b32 s1, v255, 13
	s_mov_b32 s1, s39
	v_writelane_b32 v255, s0, 12
	s_lshl_b32 s38, s70, 6
	s_lshl_b32 s4, s70, 9
	v_writelane_b32 v255, s1, 13
	v_writelane_b32 v255, s2, 16
	v_writelane_b32 v255, s10, 17
	s_mov_b32 s5, s39
	s_lshl_b64 s[4:5], s[4:5], 2
	v_writelane_b32 v255, s11, 18
	v_writelane_b32 v255, s12, 19
	s_lshl_b32 s0, s70, 8
	s_mov_b32 s1, s39
	v_writelane_b32 v255, s13, 20
	s_lshl_b64 s[12:13], s[38:39], 2
	v_writelane_b32 v255, s12, 21
	s_lshl_b64 s[0:1], s[0:1], 2
	s_lshl_b64 s[6:7], s[70:71], 19
	v_writelane_b32 v255, s13, 22
	v_writelane_b32 v255, s4, 23
	s_mov_b32 s2, 0
	s_mov_b64 s[10:11], -1
	v_writelane_b32 v255, s5, 24
	v_writelane_b32 v255, s0, 25
	s_waitcnt lgkmcnt(0)
	s_barrier
	v_writelane_b32 v255, s1, 26
	s_lshl_b64 s[0:1], s[6:7], 1
	v_writelane_b32 v255, s0, 27
	s_nop 1
	v_writelane_b32 v255, s1, 28
	s_branch .LBB0_336

.Lxb_noinv_2:
	v_cmp_eq_u32_e32 vcc, 0, v0
	s_and_saveexec_b64 s[0:1], vcc
	s_xor_b64 s[0:1], exec, s[0:1]
	s_cbranch_execz .LBB0_438
	s_load_dwordx2 s[12:13], s[8:9], 0x98
	v_readlane_b32 s14, v255, 0
	v_readlane_b32 s15, v255, 45
	s_nop 0
	s_lshr_b32 s24, s14, 3
	s_and_b32 s24, s24, 7
	s_and_b32 s27, s14, 6
	s_lshl_b32 s27, s27, 2
	s_or_b32 s27, s27, s24
	s_and_b32 s30, s14, 3
	s_lshl_b32 s30, s30, 3
	s_or_b32 s30, s30, s24
	s_lshl_b32 s27, s27, 1
	s_and_b32 s24, s14, 1
	s_or_b32 s27, s27, s24
	s_lshl_b32 s27, s27, 7
	s_add_u32 s27, s27, 0x8000
	s_lshl_b32 s30, s30, 1
	s_bfe_u32 s24, s14, 0x10002
	s_or_b32 s30, s30, s24
	s_lshl_b32 s30, s30, 7
	s_add_u32 s30, s30, 0x8000
	s_add_u32 s15, s15, 4
	v_writelane_b32 v255, s15, 45
	v_mov_b32_e32 v0, s27
	s_waitcnt lgkmcnt(0)
	global_atomic_add v0, v189, s[12:13]
	s_cmp_lt_u32 s14, 0xc0
	s_cbranch_scc1 .Lgs_nocw_b2
	v_mov_b32_e32 v10, 0xd000
	global_atomic_add v10, v189, s[12:13]
.Lgs_nocw_b2:
	v_mov_b32_e32 v7, s30
	s_mov_b32 s32, 0
